# skip the unread bf16 stream copy of the last layer (phase 29); reverted QK pipelining and relaxed waits (no measurable gain)
# speedup vs baseline: 1.0193x; 1.0035x over previous
.LBB0_908:
	s_add_i32 m0, s31, 0x18000
	v_lshl_add_u64 v[12:13], v[12:13], 0, s[16:17]
	s_waitcnt vmcnt(4)
	s_barrier
	global_load_lds_dwordx4 v[12:13], off
	v_lshl_add_u64 v[10:11], v[10:11], 0, s[16:17]
	s_add_i32 m0, s31, 0x1a000
	s_add_i32 s97, s31, 0x8000
	global_load_lds_dwordx4 v[10:11], off
	v_lshl_add_u64 v[8:9], v[8:9], 0, s[16:17]
	s_mov_b32 m0, s97
	s_add_i32 s90, s31, 0xa000
	global_load_lds_dwordx4 v[8:9], off
	v_lshl_add_u64 v[6:7], v[6:7], 0, s[16:17]
	s_mov_b32 m0, s90
	v_lshl_add_u64 v[4:5], v[4:5], 0, s[16:17]
	global_load_lds_dwordx4 v[6:7], off
	s_add_i32 m0, s31, 0x1c000
	v_lshl_add_u64 v[2:3], v[2:3], 0, s[16:17]
	global_load_lds_dwordx4 v[4:5], off
	s_add_i32 m0, s31, 0x1e000
	s_lshr_b32 s91, s94, 6
	global_load_lds_dwordx4 v[2:3], off
	s_and_b32 s4, s4, 3
	s_waitcnt vmcnt(0)
	v_lshl_or_b32 v210, s42, 6, v206
	s_lshl_b32 s42, s42, 13
	v_lshlrev_b32_e32 v2, 2, v206
	s_add_i32 s66, s91, -2
	v_lshl_or_b32 v0, v206, 6, v208
	v_and_b32_e32 v2, 32, v2
	s_cmp_lt_u32 s4, 2
	v_bitop3_b32 v2, v0, s42, v2 bitop3:0xde
	s_cselect_b64 s[42:43], -1, 0
	v_lshl_or_b32 v162, s4, 5, v207
	v_writelane_b32 v253, s42, 57
	s_cmp_eq_u32 s4, 0
	s_waitcnt vmcnt(6)
	v_lshlrev_b32_e32 v0, 2, v162
	v_writelane_b32 v253, s43, 58
	s_cselect_b64 s[42:43], -1, 0
	s_cmp_lg_u64 s[48:49], 0
	v_writelane_b32 v253, s42, 55
	v_lshl_add_u64 v[176:177], s[38:39], 0, v[0:1]
	v_lshlrev_b32_e32 v0, 1, v162
	s_cselect_b64 s[68:69], -1, 0
	s_cmp_eq_u32 s74, 29
	s_cselect_b64 s[68:69], 0, s[68:69]
	s_cmp_lg_u64 s[56:57], 0
	v_lshl_or_b32 v211, s4, 12, v209
	s_mov_b32 s67, 0
	v_writelane_b32 v253, s43, 56
	v_lshl_add_u64 v[178:179], s[58:59], 0, v[0:1]
	v_lshl_add_u64 v[180:181], s[24:25], 0, v[0:1]
	s_cselect_b64 s[70:71], -1, 0
	v_lshl_add_u64 v[182:183], s[60:61], 0, v[172:173]
	v_lshl_add_u64 v[184:185], s[60:61], 0, v[168:169]
	v_add_u32_e32 v212, 0, v2
	s_barrier
	s_branch .LBB0_910
